# conversion engine in P1 K-loop: per-wave stagger of the 4-iteration item cycle (gw&3) so HBM bursts are spread over iterations
# baseline (speedup 1.0000x reference)
; #define PG8_STAGE(bufoff, gbase, voff) do { _Pragma("unroll") for (int _i = 0; _i < 2; ++_i) \
;         __builtin_amdgcn_global_load_lds((const unsigned*)((const char*)(gbase) + (voff)[_i]), (PG8_LAS unsigned*)(lds + (bufoff) + ldsw + _i * 8192), 16, 0, 0); } while (0)
; #define PG8_WAIT_V(n) asm volatile("s_waitcnt vmcnt(" #n ")" ::: "memory")
; #define PG8_BAR __builtin_amdgcn_s_barrier()
; template <class Epi, class Sched, bool ALIGN_EPI = false, bool SP2 = false>
; __device__ __forceinline__ void gemm_phase(PG8_LAS unsigned char* lds, const Gemm g, const Sched& S, const Epi& E) {
;     const int tid = threadIdx.x, wid = __builtin_amdgcn_readfirstlane(tid >> 6), lane = tid & 63, wr = wid >> 2, wc = wid & 3, fr = lane & 15, fq = lane >> 4;
;     const int K = g.K, nt = K / BK;
;     unsigned voffA[2], voffB[2];
; #pragma unroll
;     for (int i = 0; i < 2; ++i) { int R, C; stage_rc(tid * 16 + i * 8192, R, C); const int Rb = Epi::PERM ? ((R & ~31) + perm32(R & 31)) : R;
;         voffA[i] = (unsigned)(R * g.lda + C) * 2u; voffB[i] = (unsigned)(Rb * g.ldb + C) * 2u; }
;     const size_t kstep = (size_t)(BK * 2);
;     const size_t hstepA = (size_t)HALF * g.lda * 2, hstepB = (size_t)HALF * g.ldb * 2;
;     const size_t tstepA = 2 * hstepA, tstepB = 2 * hstepB;
;     const unsigned ldsw = (unsigned)wid * 1024u;
;     const int aoff = lds_byte(wr * 64 + fr, fq * 8), boff = lds_byte(wc * 32 + fr, fq * 8);
;     ...
;         PG8_STAGE(PG8_SB(1, 0), cB + kstep, voffB); PG8_STAGE(PG8_SA(1, 0), cA + kstep, voffA); PG8_STAGE(PG8_SB(1, 1), cB + hstepB + kstep, voffB);
;         PG8_WAIT_V(6); PG8_BAR;
.LBB0_137:
	s_lshl_b32 s5, s5, 5
	s_mov_b64 s[18:19], 0x80
	s_and_b32 s5, s5, 0x60
	s_add_i32 m0, s55, 0x18000
	v_lshl_add_u64 v[8:9], v[8:9], 0, s[18:19]
	s_lshl_b32 s1, s4, 13
	s_lshl_b32 s22, s5, 7
	s_waitcnt vmcnt(2)
	s_barrier
	global_load_lds_dwordx4 v[8:9], off
	v_lshl_add_u64 v[4:5], v[4:5], 0, s[18:19]
	s_add_i32 m0, s55, 0x1a000
	s_add_i32 s75, s55, 0x8000
	s_add_i32 s76, s55, 0xa000
	global_load_lds_dwordx4 v[4:5], off
	v_lshl_add_u64 v[2:3], v[2:3], 0, s[18:19]
	s_mov_b32 m0, s75
	s_add_u32 s20, s8, 0x100080
	global_load_lds_dwordx4 v[2:3], off
	v_lshl_add_u64 v[2:3], v[6:7], 0, s[18:19]
	s_mov_b32 m0, s76
	s_addc_u32 s21, s9, 0
	global_load_lds_dwordx4 v[2:3], off
	s_add_i32 m0, s55, 0x1c000
	v_lshl_add_u64 v[2:3], s[20:21], 0, v[140:141]
	global_load_lds_dwordx4 v[2:3], off
	v_lshl_add_u64 v[2:3], s[20:21], 0, v[144:145]
	s_add_i32 m0, s55, 0x1e000
	v_and_b32_e32 v4, 32, v162
	global_load_lds_dwordx4 v[2:3], off
	v_and_b32_e32 v2, 15, v0
	v_lshlrev_b32_e32 v3, 1, v14
	v_lshl_or_b32 v163, s4, 6, v2
	v_lshl_or_b32 v2, v2, 6, v3
	v_bitop3_b32 v2, v2, s1, v4 bitop3:0xde
	v_lshlrev_b32_e32 v5, 6, v0
	s_movk_i32 s1, 0x3c0
	v_and_or_b32 v3, v5, s1, v3
	v_bitop3_b32 v164, s22, v3, v4 bitop3:0xf6
	v_lshlrev_b32_e32 v3, 10, v0
	v_and_b32_e32 v3, 0x60000, v3
	v_lshlrev_b32_e32 v4, 13, v12
	v_or3_b32 v3, v10, v3, v4
	s_cmpk_lt_u32 s14, 0x100
	v_add_u32_e32 v148, v3, v11
	v_lshlrev_b32_e32 v3, 6, v13
	s_waitcnt vmcnt(6)
	s_cselect_b64 s[20:21], -1, 0
	s_add_u32 s22, s62, 0x2000
	v_and_b32_e32 v3, 0xe0000, v3
	v_or_b32_e32 v165, s5, v14
	s_addc_u32 s23, s63, 0
	v_or3_b32 v3, v10, v3, v4
	s_add_i32 s83, 0, 0x10000
	s_add_i32 s89, 0, 0x14000
	v_or_b32_e32 v166, 0xffffec00, v165
	s_ashr_i32 s77, s74, 31
	s_ashr_i32 s81, s2, 31
	v_mov_b32_e32 v149, v147
	v_add_u32_e32 v150, v3, v11
	v_mov_b32_e32 v151, v147
	v_mov_b64_e32 v[152:153], 0x900
	v_mov_b64_e32 v[154:155], 0x8ff
	v_add_u32_e32 v167, s83, v164
	v_add_u32_e32 v168, s89, v164
	v_add_u32_e32 v169, 0, v2
	s_mov_b32 s90, 0xc2a00000
	s_mov_b32 s91, 0xc1f00000
	v_mov_b32_e32 v170, 0x42a00000
	v_mov_b32_e32 v171, 0x41f00000
	s_mov_b32 s92, 0
	s_barrier
	s_and_b32 s32, s80, 3
	s_sub_i32 s32, 0, s32
	s_mov_b32 s97, 0
	v_readlane_b32 s98, v244, 0
	v_readlane_b32 s99, v244, 1
	s_nop 3
	s_sub_u32 s98, s98, 0x98
	s_subb_u32 s99, s99, 0
	s_load_dwordx2 s[100:101], s[98:99], 0x58
	s_waitcnt lgkmcnt(0)
	v_writelane_b32 v245, s100, 0
	v_writelane_b32 v245, s101, 1
	s_nop 1
	s_load_dwordx2 s[100:101], s[98:99], 0x60
	s_waitcnt lgkmcnt(0)
	v_writelane_b32 v245, s100, 2
	v_writelane_b32 v245, s101, 3
	s_nop 1
	s_load_dwordx2 s[100:101], s[98:99], 0x50
	s_waitcnt lgkmcnt(0)
	v_writelane_b32 v245, s100, 4
	v_writelane_b32 v245, s101, 5
	s_nop 1
	s_load_dwordx2 s[100:101], s[98:99], 0x38
	s_waitcnt lgkmcnt(0)
	v_writelane_b32 v245, s100, 6
	v_writelane_b32 v245, s101, 7
	s_nop 1
	s_load_dwordx2 s[100:101], s[98:99], 0x40
	s_waitcnt lgkmcnt(0)
	v_writelane_b32 v245, s100, 8
	v_writelane_b32 v245, s101, 9
	s_nop 1
	s_load_dwordx2 s[100:101], s[98:99], 0x48
	s_waitcnt lgkmcnt(0)
	v_writelane_b32 v245, s100, 10
	v_writelane_b32 v245, s101, 11
	s_mul_hi_u32 s93, s80, 0xbe82fa0c
	s_lshr_b32 s93, s93, 8
	s_mul_i32 s85, s93, 0x158
	s_sub_i32 s85, s80, s85
	s_lshl_b32 s93, s93, 16
	s_or_b32 s85, s85, s93
	s_mov_b64 s[100:101], 0
	s_branch .LBB0_140

.LBB0_143:
	s_add_i32 s32, s32, 1
	s_mov_b32 s97, 0
	s_cmp_lt_i32 s32, 1
	s_cbranch_scc1 .Leng_done
	s_sub_i32 s93, s32, 1
	s_and_b32 s93, s93, 3
	s_cmp_lg_u32 s93, 0
	s_cbranch_scc1 .Leng_not0
	s_mov_b64 s[100:101], 0
	s_bitcmp1_b32 s85, 31
	s_cbranch_scc1 .Leng_grpB
	s_lshr_b32 s93, s85, 16
	s_cmp_ge_u32 s93, 0x100
	s_cbranch_scc0 .Leng_Aok
	s_or_b32 s85, s80, 0x80000000
	s_branch .Leng_grpB
